# adds: MoE tile->list linear search resumes from the previous tile's list index (tile index is monotonic per workgroup)
# speedup vs baseline: 1.0510x; 1.0019x over previous
; #define RUN(k, call) if (lo <= (k) && (k) < hi) { if ((k) > lo) grid.sync(); if (PHMASK & (1 << (k))) { call; } }
; __global__ void __launch_bounds__(NT, 2) fwd_kernel(Params p) {
;     ...
;   RUN(0, phase0(p, lds))
;   RUN(1, phase1(p))
;   RUN(2, phase2(p, lds))
;   RUN(3, phase3(p, lds))
;   RUN(4, phase4(p, lds))
;   RUN(5, phase5(p, lds))
;   RUN(6, phase_moe(p, lds, 0))
.LBB0_268:
	s_mov_b32 s98, 0
	s_cmp_gt_i32 s78, 6
	s_cselect_b64 s[6:7], -1, 0
	s_cmp_lt_i32 s78, 7
	s_cselect_b64 s[0:1], -1, 0
	s_cmp_gt_i32 s79, 6
	s_cselect_b64 s[4:5], -1, 0
	s_and_b64 s[0:1], s[0:1], s[4:5]
	s_andn2_b64 vcc, exec, s[0:1]
	s_cbranch_vccnz .LBB0_302
	s_andn2_b64 vcc, exec, s[20:21]
	s_cbranch_vccnz .LBB0_271
	v_and_b32_e32 v1, 0x3ff, v0
	s_cbranch_execz .LBB0_272
	s_branch .LBB0_283

; DI void phase_moe(const Params& p, char* lds, int mode) {
;     ...
;     int sl = 0;
;     while (pre[sl + 1] <= tile) ++sl;
;     const int li = mode == 0 ? sl : sl * 2 + (mode - 1);
;     const int e = li >> 1, k = li & 1;
;     const int r0 = (tile - pre[sl]) * 256, n = cnt[li];
;     if (tid < 256) { int idx = r0 + tid; if (idx >= n) idx = n - 1; rowtok[tid] = list[(size_t)li * T + idx]; }
.LBB0_294:
	s_add_i32 s16, s98, -1
	s_lshl_b32 s39, s98, 2
	s_add_i32 s39, s39, 0x21004
	s_mov_b32 s26, s98
	s_mov_b32 s27, 0
.LBB0_295:
	v_mov_b32_e32 v2, s39
	ds_read_b32 v2, v2
	s_mov_b64 s[24:25], s[26:27]
	s_add_i32 s16, s16, 1
	s_add_i32 s39, s39, 4
	s_add_u32 s26, s24, 1
	s_waitcnt lgkmcnt(0)
	v_cmp_ge_i32_e32 vcc, s38, v2
	s_addc_u32 s27, s25, 0
	s_cbranch_vccnz .LBB0_295
	s_mov_b32 s98, s16
	s_lshl_b32 s39, s16, 2
	s_add_i32 s40, s39, 0x21000
	s_lshl_b64 s[26:27], s[16:17], 2
	s_add_u32 s26, s8, s26
	s_addc_u32 s27, s9, s27
	global_load_dword v167, v151, s[26:27]
	v_mov_b32_e32 v2, s40
	ds_read_b32 v2, v2
	s_waitcnt lgkmcnt(0)
	v_sub_u32_e32 v2, s38, v2
	v_lshlrev_b32_e32 v168, 8, v2
	s_and_saveexec_b64 s[26:27], s[4:5]
	s_cbranch_execz .LBB0_298
	v_or_b32_e32 v2, v168, v1
	s_waitcnt vmcnt(0)
	v_add_u32_e32 v3, -1, v167
	s_mul_i32 s40, s16, 0x60000
	v_min_i32_e32 v2, v2, v3
	s_mul_hi_u32 s41, s16, 0x60000
	s_add_u32 s40, s30, s40
	v_ashrrev_i32_e32 v3, 31, v2
	s_addc_u32 s41, s31, s41
	v_lshl_add_u64 v[2:3], v[2:3], 2, s[40:41]
	global_load_dword v2, v[2:3], off
	s_waitcnt vmcnt(0)
	ds_write_b32 v157, v2

; #define RUN(k, call) if (lo <= (k) && (k) < hi) { if ((k) > lo) grid.sync(); if (PHMASK & (1 << (k))) { call; } }
; __global__ void __launch_bounds__(NT, 2) fwd_kernel(Params p) {
;     ...
;   RUN(0, phase0(p, lds))
;   RUN(1, phase1(p))
;   RUN(2, phase2(p, lds))
;   RUN(3, phase3(p, lds))
;   RUN(4, phase4(p, lds))
;   RUN(5, phase5(p, lds))
;   RUN(6, phase_moe(p, lds, 0))
;   RUN(7, phase_moe(p, lds, 1))
.LBB0_302:
	s_mov_b32 s98, 0
	s_cmp_gt_i32 s78, 7
	s_waitcnt lgkmcnt(0)
	s_cselect_b64 s[12:13], -1, 0
	s_cmp_lt_i32 s78, 8
	s_cselect_b64 s[0:1], -1, 0
	s_cmp_gt_i32 s79, 7
	s_cselect_b64 s[4:5], -1, 0
	s_and_b64 s[0:1], s[0:1], s[4:5]
	s_andn2_b64 vcc, exec, s[0:1]
	s_cbranch_vccnz .LBB0_397
	s_andn2_b64 vcc, exec, s[6:7]
	s_cbranch_vccnz .LBB0_305
	v_and_b32_e32 v1, 0x3ff, v0
	s_cbranch_execz .LBB0_306
	s_branch .LBB0_317

; DI void phase_moe(const Params& p, char* lds, int mode) {
;     ...
;     int sl = 0;
;     while (pre[sl + 1] <= tile) ++sl;
;     const int li = mode == 0 ? sl : sl * 2 + (mode - 1);
;     const int e = li >> 1, k = li & 1;
;     const int r0 = (tile - pre[sl]) * 256, n = cnt[li];
;     if (tid < 256) { int idx = r0 + tid; if (idx >= n) idx = n - 1; rowtok[tid] = list[(size_t)li * T + idx]; }
.LBB0_328:
	s_add_i32 s4, s98, -1
	s_lshl_b32 s5, s98, 2
	s_add_i32 s5, s5, 0x21004
.LBB0_329:
	v_mov_b32_e32 v2, s5
	ds_read_b32 v2, v2
	s_add_i32 s4, s4, 1
	s_add_i32 s5, s5, 4
	s_waitcnt lgkmcnt(0)
	v_cmp_ge_i32_e32 vcc, s66, v2
	s_cbranch_vccnz .LBB0_329
	s_mov_b32 s98, s4
	s_lshl_b32 s52, s4, 1
	s_lshl_b32 s5, s4, 2
	s_add_i32 s5, s5, 0x21000
	s_lshl_b64 s[6:7], s[52:53], 2
	s_add_u32 s6, s44, s6
	s_addc_u32 s7, s45, s7
	global_load_dword v172, v131, s[6:7]
	v_mov_b32_e32 v2, s5
	ds_read_b32 v2, v2
	s_waitcnt lgkmcnt(0)
	v_sub_u32_e32 v2, s66, v2
	v_lshlrev_b32_e32 v173, 8, v2
	s_and_saveexec_b64 s[6:7], s[36:37]
	s_cbranch_execz .LBB0_332
	v_or_b32_e32 v2, v173, v1
	s_waitcnt vmcnt(0)
	v_add_u32_e32 v3, -1, v172
	s_mul_i32 s8, s52, 0x60000
	v_readlane_b32 s9, v247, 9
	v_min_i32_e32 v2, v2, v3
	s_mul_hi_u32 s5, s52, 0x60000
	s_add_u32 s8, s9, s8
	v_readlane_b32 s9, v247, 10
	v_ashrrev_i32_e32 v3, 31, v2
	s_addc_u32 s9, s9, s5
	v_lshl_add_u64 v[2:3], v[2:3], 2, s[8:9]
	global_load_dword v2, v[2:3], off
	s_waitcnt vmcnt(0)
	ds_write_b32 v144, v2

; #define RUN(k, call) if (lo <= (k) && (k) < hi) { if ((k) > lo) grid.sync(); if (PHMASK & (1 << (k))) { call; } }
; __global__ void __launch_bounds__(NT, 2) fwd_kernel(Params p) {
;     ...
;   RUN(0, phase0(p, lds))
;   RUN(1, phase1(p))
;   RUN(2, phase2(p, lds))
;   RUN(3, phase3(p, lds))
;   RUN(4, phase4(p, lds))
;   RUN(5, phase5(p, lds))
;   RUN(6, phase_moe(p, lds, 0))
;   RUN(7, phase_moe(p, lds, 1))
;   RUN(8, phase_moe(p, lds, 2))
.LBB0_397:
	s_mov_b32 s98, 0
	s_cmp_lt_i32 s78, 9
	s_cselect_b64 s[0:1], -1, 0
	s_cmp_gt_i32 s79, 8
	s_cselect_b64 s[4:5], -1, 0
	s_and_b64 s[0:1], s[0:1], s[4:5]
	s_andn2_b64 vcc, exec, s[0:1]
	s_cbranch_vccnz .LBB0_492
	s_andn2_b64 vcc, exec, s[12:13]
	s_cbranch_vccnz .LBB0_400
	v_and_b32_e32 v186, 0x3ff, v0
	s_cbranch_execz .LBB0_401
	s_branch .LBB0_412

; DI void phase_moe(const Params& p, char* lds, int mode) {
;     ...
;     int sl = 0;
;     while (pre[sl + 1] <= tile) ++sl;
;     const int li = mode == 0 ? sl : sl * 2 + (mode - 1);
;     const int e = li >> 1, k = li & 1;
;     const int r0 = (tile - pre[sl]) * 256, n = cnt[li];
;     if (tid < 256) { int idx = r0 + tid; if (idx >= n) idx = n - 1; rowtok[tid] = list[(size_t)li * T + idx]; }
.LBB0_422:
	s_add_i32 s4, s98, -1
	s_lshl_b32 s0, s98, 2
	s_add_i32 s0, s0, 0x21004
.LBB0_423:
	s_waitcnt vmcnt(1)
	v_mov_b32_e32 v0, s0
	ds_read_b32 v0, v0
	s_add_i32 s4, s4, 1
	s_add_i32 s0, s0, 4
	s_waitcnt lgkmcnt(0)
	v_cmp_ge_i32_e32 vcc, s67, v0
	s_cbranch_vccnz .LBB0_423
	s_mov_b32 s98, s4
	s_lshl_b32 s0, s4, 1
	s_or_b32 s48, s0, 1
	s_lshl_b32 s0, s4, 2
	s_add_i32 s5, s0, 0x21000
	s_lshl_b64 s[0:1], s[48:49], 2
	s_add_u32 s0, s38, s0
	s_addc_u32 s1, s39, s1
	global_load_dword v145, v129, s[0:1]
	v_mov_b32_e32 v0, s5
	ds_read_b32 v0, v0
	s_waitcnt lgkmcnt(0)
	v_sub_u32_e32 v0, s67, v0
	v_lshlrev_b32_e32 v153, 8, v0
	s_and_saveexec_b64 s[0:1], s[34:35]
	s_cbranch_execz .LBB0_426
	v_or_b32_e32 v0, v153, v186
	s_waitcnt vmcnt(0)
	v_add_u32_e32 v1, -1, v145
	s_mul_i32 s6, s48, 0x60000
	v_readlane_b32 s7, v247, 9
	v_min_i32_e32 v0, v0, v1
	s_mul_hi_u32 s5, s48, 0x60000
	s_add_u32 s6, s7, s6
	v_readlane_b32 s7, v247, 10
	v_ashrrev_i32_e32 v1, 31, v0
	s_addc_u32 s7, s7, s5
	v_lshl_add_u64 v[0:1], v[0:1], 2, s[6:7]
	global_load_dword v0, v[0:1], off
	s_waitcnt vmcnt(0)
	ds_write_b32 v187, v0
